# de-serialised gate-load/store epilogues of both attention mixers (16 loads in flight, counted waits) + mixer B queue dealt in descending order
# speedup vs baseline: 1.6338x; 1.6338x over previous
; DI bool attn_next(AttnQueue& q, int lane0, int& qs, int& hd) {
;     for (;;) {
;         if (q.cur >= 8) return false;
;         const int xq = (q.x + q.cur) & 7;
;         const int nqs = NQS / 8 + (xq == 7 ? 1 : 0);
;         unsigned n = 0;
;         if (lane0) n = __hip_atomic_fetch_add(q.heads + 64 * xq, 1u, __ATOMIC_RELAXED, __HIP_MEMORY_SCOPE_AGENT);
;         n = (unsigned)__builtin_amdgcn_readfirstlane((int)n);
;         if (n < (unsigned)(nqs * 16)) { qs = (NQS / 8) * xq + (int)(n >> 4); hd = (int)(n & 15u); return true; }
;         ++q.cur;
;     }
; }
.LBB0_141:
	s_andn2_b64 vcc, exec, s[4:5]
	s_cbranch_vccnz .LBB0_133
	s_lshl_b32 s4, s8, 6
	s_lshr_b32 s5, s6, 4
	s_sub_i32 s7, 63, s5
	s_cmp_lt_u32 s5, 64
	s_cselect_b32 s5, s7, s5
	s_add_i32 s24, s5, s4
	s_and_b32 s23, s6, 15
	s_mov_b32 s7, s26
	s_branch .LBB0_133

; DI unsigned pk2(float a, float b) { f32x2 v = {a, b}; bf16v2 r = __builtin_convertvector(v, bf16v2); return __builtin_bit_cast(unsigned, r); }
; DI float bf_lo(unsigned u) { return __uint_as_float(u << 16); }
; DI float bf_hi(unsigned u) { return __uint_as_float(u & 0xffff0000u); }
; DI size_t zrowU(int row0, int NT) { return ((size_t)((row0 >> 8) * NT) << 16) + (size_t)((((row0 >> 7) & 1) << 15) | (((row0 >> 5) & 1) << 14) | (((row0 >> 6) & 1) << 11)); }
; DI unsigned zlaneRC(int r5, int col) { return (unsigned)(((col >> 8) << 16) | ((r5 >> 4) << 13) | (((col >> 7) & 1) << 12) | (((col >> 5) & 3) << 9) | (((col >> 3) & 3) << 7) | ((r5 & 15) << 3) | (col & 7)); }
; DI float silu_mul(float o, float g) { return o * g * __builtin_amdgcn_rcpf(1.0f + __builtin_amdgcn_exp2f(g * -1.4426950408889634f)); }
; DI void attnB_item(bf16_t* z, int hh, int qs, LAS bf16_t* vs, int lane) {
;     ...
;     if (!metaq || c < NMETA) {
;         bf16_t* orow = z + zrowU(qrow0, 32) + zlaneRC(c, hh * 128 + 4 * h);
;         const bf16_t* grow = z + zrowU(qrow0, 32) + zlaneRC(c, 6144 + hh * 128 + 4 * h);
; #pragma unroll
;         for (int dt = 0; dt < 4; ++dt)
; #pragma unroll
;             for (int g = 0; g < 4; ++g) {
;                 const int d0 = (dt << 9) | (g << 7);
;                 const u32x2 gv = *(const u32x2*)(grow + d0);
;                 u32x2 o; o.x = pk2(silu_mul(acc[dt][4 * g], bf_lo(gv.x)), silu_mul(acc[dt][4 * g + 1], bf_hi(gv.x)));
;                 o.y = pk2(silu_mul(acc[dt][4 * g + 2], bf_lo(gv.y)), silu_mul(acc[dt][4 * g + 3], bf_hi(gv.y)));
;                 *(u32x2*)(orow + d0) = o;
;             }
;     }
.LBB0_157:
	v_cmp_gt_u32_e32 vcc, 16, v178
	s_or_b64 s[0:1], s[0:1], vcc
	s_and_saveexec_b64 s[4:5], s[0:1]
	s_xor_b64 s[0:1], exec, s[4:5]
	s_cbranch_execz .LBB0_130
	v_add_u32_e32 v0, s27, v183
	v_lshlrev_b32_e32 v66, 8, v0
	v_lshlrev_b32_e32 v0, 5, v0
	v_lshlrev_b32_e32 v67, 6, v180
	v_and_b32_e32 v0, 0x1000, v0
	v_and_b32_e32 v68, 0x780, v67
	v_and_b32_e32 v69, 4, v183
	v_or_b32_e32 v67, v68, v69
	v_and_or_b32 v70, v66, s12, v0
	v_or3_b32 v0, v67, v181, v70
	v_lshl_add_u64 v[146:147], v[0:1], 1, s[46:47]
	v_or3_b32 v0, v70, v69, v68
	s_mov_b32 s4, 0x180000
	v_add3_u32 v0, v0, v181, s4
	v_lshl_add_u64 v[148:149], v[0:1], 1, s[46:47]
	global_load_dwordx2 v[192:193], v[148:149], off
	global_load_dwordx2 v[194:195], v[148:149], off offset:256
	global_load_dwordx2 v[196:197], v[148:149], off offset:512
	global_load_dwordx2 v[198:199], v[148:149], off offset:768
	global_load_dwordx2 v[200:201], v[148:149], off offset:1024
	global_load_dwordx2 v[202:203], v[148:149], off offset:1280
	global_load_dwordx2 v[204:205], v[148:149], off offset:1536
	global_load_dwordx2 v[206:207], v[148:149], off offset:1792
	global_load_dwordx2 v[208:209], v[148:149], off offset:2048
	global_load_dwordx2 v[210:211], v[148:149], off offset:2304
	global_load_dwordx2 v[212:213], v[148:149], off offset:2560
	global_load_dwordx2 v[214:215], v[148:149], off offset:2816
	global_load_dwordx2 v[216:217], v[148:149], off offset:3072
	global_load_dwordx2 v[218:219], v[148:149], off offset:3328
	global_load_dwordx2 v[220:221], v[148:149], off offset:3584
	global_load_dwordx2 v[222:223], v[148:149], off offset:3840
	s_waitcnt vmcnt(15)
	v_lshlrev_b32_e32 v66, 16, v192
	v_and_b32_e32 v67, 0xffff0000, v192
	v_lshlrev_b32_e32 v68, 16, v193
	v_and_b32_e32 v69, 0xffff0000, v193
	v_mul_f32_e32 v70, 0xbfb8aa3b, v66
	v_mul_f32_e32 v71, 0xbfb8aa3b, v67
	v_mul_f32_e32 v72, 0xbfb8aa3b, v68
	v_mul_f32_e32 v73, 0xbfb8aa3b, v69
	v_exp_f32_e32 v70, v70
	v_exp_f32_e32 v71, v71
	v_exp_f32_e32 v72, v72
	v_exp_f32_e32 v73, v73
	v_pk_mul_f32 v[50:51], v[50:51], v[66:67]
	v_pk_mul_f32 v[52:53], v[52:53], v[68:69]
	v_add_f32_e32 v70, 1.0, v70
	v_add_f32_e32 v71, 1.0, v71
	v_add_f32_e32 v72, 1.0, v72
	v_add_f32_e32 v73, 1.0, v73
	v_rcp_f32_e32 v70, v70
	v_rcp_f32_e32 v71, v71
	v_rcp_f32_e32 v72, v72
	v_rcp_f32_e32 v73, v73
	v_pk_mul_f32 v[50:51], v[50:51], v[70:71]
	v_pk_mul_f32 v[52:53], v[52:53], v[72:73]
	v_cvt_pk_bf16_f32 v50, v50, v51
	v_cvt_pk_bf16_f32 v51, v52, v53
	s_waitcnt vmcnt(14)
	v_lshlrev_b32_e32 v74, 16, v194
	v_and_b32_e32 v75, 0xffff0000, v194
	v_lshlrev_b32_e32 v76, 16, v195
	v_and_b32_e32 v77, 0xffff0000, v195
	v_mul_f32_e32 v78, 0xbfb8aa3b, v74
	v_mul_f32_e32 v79, 0xbfb8aa3b, v75
	v_mul_f32_e32 v80, 0xbfb8aa3b, v76
	v_mul_f32_e32 v81, 0xbfb8aa3b, v77
	v_exp_f32_e32 v78, v78
	v_exp_f32_e32 v79, v79
	v_exp_f32_e32 v80, v80
	v_exp_f32_e32 v81, v81
	v_pk_mul_f32 v[54:55], v[54:55], v[74:75]
	v_pk_mul_f32 v[56:57], v[56:57], v[76:77]
	v_add_f32_e32 v78, 1.0, v78
	v_add_f32_e32 v79, 1.0, v79
	v_add_f32_e32 v80, 1.0, v80
	v_add_f32_e32 v81, 1.0, v81
	v_rcp_f32_e32 v78, v78
	v_rcp_f32_e32 v79, v79
	v_rcp_f32_e32 v80, v80
	v_rcp_f32_e32 v81, v81
	v_pk_mul_f32 v[54:55], v[54:55], v[78:79]
	v_pk_mul_f32 v[56:57], v[56:57], v[80:81]
	v_cvt_pk_bf16_f32 v54, v54, v55
	v_cvt_pk_bf16_f32 v55, v56, v57
	s_waitcnt vmcnt(13)
	v_lshlrev_b32_e32 v66, 16, v196
	v_and_b32_e32 v67, 0xffff0000, v196
	v_lshlrev_b32_e32 v68, 16, v197
	v_and_b32_e32 v69, 0xffff0000, v197
	v_mul_f32_e32 v70, 0xbfb8aa3b, v66
	v_mul_f32_e32 v71, 0xbfb8aa3b, v67
	v_mul_f32_e32 v72, 0xbfb8aa3b, v68
	v_mul_f32_e32 v73, 0xbfb8aa3b, v69
	v_exp_f32_e32 v70, v70
	v_exp_f32_e32 v71, v71
	v_exp_f32_e32 v72, v72
	v_exp_f32_e32 v73, v73
	v_pk_mul_f32 v[58:59], v[58:59], v[66:67]
	v_pk_mul_f32 v[60:61], v[60:61], v[68:69]
	v_add_f32_e32 v70, 1.0, v70
	v_add_f32_e32 v71, 1.0, v71
	v_add_f32_e32 v72, 1.0, v72
	v_add_f32_e32 v73, 1.0, v73
	v_rcp_f32_e32 v70, v70
	v_rcp_f32_e32 v71, v71
	v_rcp_f32_e32 v72, v72
	v_rcp_f32_e32 v73, v73
	v_pk_mul_f32 v[58:59], v[58:59], v[70:71]
	v_pk_mul_f32 v[60:61], v[60:61], v[72:73]
	v_cvt_pk_bf16_f32 v58, v58, v59
	v_cvt_pk_bf16_f32 v59, v60, v61
	s_waitcnt vmcnt(12)
	v_lshlrev_b32_e32 v74, 16, v198
	v_and_b32_e32 v75, 0xffff0000, v198
	v_lshlrev_b32_e32 v76, 16, v199
	v_and_b32_e32 v77, 0xffff0000, v199
	v_mul_f32_e32 v78, 0xbfb8aa3b, v74
	v_mul_f32_e32 v79, 0xbfb8aa3b, v75
	v_mul_f32_e32 v80, 0xbfb8aa3b, v76
	v_mul_f32_e32 v81, 0xbfb8aa3b, v77
	v_exp_f32_e32 v78, v78
	v_exp_f32_e32 v79, v79
	v_exp_f32_e32 v80, v80
	v_exp_f32_e32 v81, v81
	v_pk_mul_f32 v[62:63], v[62:63], v[74:75]
	v_pk_mul_f32 v[64:65], v[64:65], v[76:77]
	v_add_f32_e32 v78, 1.0, v78
	v_add_f32_e32 v79, 1.0, v79
	v_add_f32_e32 v80, 1.0, v80
	v_add_f32_e32 v81, 1.0, v81
	v_rcp_f32_e32 v78, v78
	v_rcp_f32_e32 v79, v79
	v_rcp_f32_e32 v80, v80
	v_rcp_f32_e32 v81, v81
	v_pk_mul_f32 v[62:63], v[62:63], v[78:79]
	v_pk_mul_f32 v[64:65], v[64:65], v[80:81]
	v_cvt_pk_bf16_f32 v62, v62, v63
	v_cvt_pk_bf16_f32 v63, v64, v65
	s_waitcnt vmcnt(11)
	v_lshlrev_b32_e32 v66, 16, v200
	v_and_b32_e32 v67, 0xffff0000, v200
	v_lshlrev_b32_e32 v68, 16, v201
	v_and_b32_e32 v69, 0xffff0000, v201
	v_mul_f32_e32 v70, 0xbfb8aa3b, v66
	v_mul_f32_e32 v71, 0xbfb8aa3b, v67
	v_mul_f32_e32 v72, 0xbfb8aa3b, v68
	v_mul_f32_e32 v73, 0xbfb8aa3b, v69
	v_exp_f32_e32 v70, v70
	v_exp_f32_e32 v71, v71
	v_exp_f32_e32 v72, v72
	v_exp_f32_e32 v73, v73
	v_pk_mul_f32 v[34:35], v[34:35], v[66:67]
	v_pk_mul_f32 v[36:37], v[36:37], v[68:69]
	v_add_f32_e32 v70, 1.0, v70
	v_add_f32_e32 v71, 1.0, v71
	v_add_f32_e32 v72, 1.0, v72
	v_add_f32_e32 v73, 1.0, v73
	v_rcp_f32_e32 v70, v70
	v_rcp_f32_e32 v71, v71
	v_rcp_f32_e32 v72, v72
	v_rcp_f32_e32 v73, v73
	v_pk_mul_f32 v[34:35], v[34:35], v[70:71]
	v_pk_mul_f32 v[36:37], v[36:37], v[72:73]
	v_cvt_pk_bf16_f32 v34, v34, v35
	v_cvt_pk_bf16_f32 v35, v36, v37
	s_waitcnt vmcnt(10)
; DI unsigned pk2(float a, float b) { f32x2 v = {a, b}; bf16v2 r = __builtin_convertvector(v, bf16v2); return __builtin_bit_cast(unsigned, r); }
; DI float bf_lo(unsigned u) { return __uint_as_float(u << 16); }
; DI float bf_hi(unsigned u) { return __uint_as_float(u & 0xffff0000u); }
; DI size_t zrowU(int row0, int NT) { return ((size_t)((row0 >> 8) * NT) << 16) + (size_t)((((row0 >> 7) & 1) << 15) | (((row0 >> 5) & 1) << 14) | (((row0 >> 6) & 1) << 11)); }
; DI unsigned zlaneRC(int r5, int col) { return (unsigned)(((col >> 8) << 16) | ((r5 >> 4) << 13) | (((col >> 7) & 1) << 12) | (((col >> 5) & 3) << 9) | (((col >> 3) & 3) << 7) | ((r5 & 15) << 3) | (col & 7)); }
; DI float silu_mul(float o, float g) { return o * g * __builtin_amdgcn_rcpf(1.0f + __builtin_amdgcn_exp2f(g * -1.4426950408889634f)); }
; DI void attnB_item(bf16_t* z, int hh, int qs, LAS bf16_t* vs, int lane) {
;     ...
;     if (!metaq || c < NMETA) {
;         bf16_t* orow = z + zrowU(qrow0, 32) + zlaneRC(c, hh * 128 + 4 * h);
;         const bf16_t* grow = z + zrowU(qrow0, 32) + zlaneRC(c, 6144 + hh * 128 + 4 * h);
; #pragma unroll
;         for (int dt = 0; dt < 4; ++dt)
; #pragma unroll
;             for (int g = 0; g < 4; ++g) {
;                 const int d0 = (dt << 9) | (g << 7);
;                 const u32x2 gv = *(const u32x2*)(grow + d0);
;                 u32x2 o; o.x = pk2(silu_mul(acc[dt][4 * g], bf_lo(gv.x)), silu_mul(acc[dt][4 * g + 1], bf_hi(gv.x)));
;                 o.y = pk2(silu_mul(acc[dt][4 * g + 2], bf_lo(gv.y)), silu_mul(acc[dt][4 * g + 3], bf_hi(gv.y)));
;                 *(u32x2*)(orow + d0) = o;
;             }
;     }
	v_lshlrev_b32_e32 v74, 16, v202
	v_and_b32_e32 v75, 0xffff0000, v202
	v_lshlrev_b32_e32 v76, 16, v203
	v_and_b32_e32 v77, 0xffff0000, v203
	v_mul_f32_e32 v78, 0xbfb8aa3b, v74
	v_mul_f32_e32 v79, 0xbfb8aa3b, v75
	v_mul_f32_e32 v80, 0xbfb8aa3b, v76
	v_mul_f32_e32 v81, 0xbfb8aa3b, v77
	v_exp_f32_e32 v78, v78
	v_exp_f32_e32 v79, v79
	v_exp_f32_e32 v80, v80
	v_exp_f32_e32 v81, v81
	v_pk_mul_f32 v[38:39], v[38:39], v[74:75]
	v_pk_mul_f32 v[40:41], v[40:41], v[76:77]
	v_add_f32_e32 v78, 1.0, v78
	v_add_f32_e32 v79, 1.0, v79
	v_add_f32_e32 v80, 1.0, v80
	v_add_f32_e32 v81, 1.0, v81
	v_rcp_f32_e32 v78, v78
	v_rcp_f32_e32 v79, v79
	v_rcp_f32_e32 v80, v80
	v_rcp_f32_e32 v81, v81
	v_pk_mul_f32 v[38:39], v[38:39], v[78:79]
	v_pk_mul_f32 v[40:41], v[40:41], v[80:81]
	v_cvt_pk_bf16_f32 v38, v38, v39
	v_cvt_pk_bf16_f32 v39, v40, v41
	s_waitcnt vmcnt(9)
	v_lshlrev_b32_e32 v66, 16, v204
	v_and_b32_e32 v67, 0xffff0000, v204
	v_lshlrev_b32_e32 v68, 16, v205
	v_and_b32_e32 v69, 0xffff0000, v205
	v_mul_f32_e32 v70, 0xbfb8aa3b, v66
	v_mul_f32_e32 v71, 0xbfb8aa3b, v67
	v_mul_f32_e32 v72, 0xbfb8aa3b, v68
	v_mul_f32_e32 v73, 0xbfb8aa3b, v69
	v_exp_f32_e32 v70, v70
	v_exp_f32_e32 v71, v71
	v_exp_f32_e32 v72, v72
	v_exp_f32_e32 v73, v73
	v_pk_mul_f32 v[42:43], v[42:43], v[66:67]
	v_pk_mul_f32 v[44:45], v[44:45], v[68:69]
	v_add_f32_e32 v70, 1.0, v70
	v_add_f32_e32 v71, 1.0, v71
	v_add_f32_e32 v72, 1.0, v72
	v_add_f32_e32 v73, 1.0, v73
	v_rcp_f32_e32 v70, v70
	v_rcp_f32_e32 v71, v71
	v_rcp_f32_e32 v72, v72
	v_rcp_f32_e32 v73, v73
	v_pk_mul_f32 v[42:43], v[42:43], v[70:71]
	v_pk_mul_f32 v[44:45], v[44:45], v[72:73]
	v_cvt_pk_bf16_f32 v42, v42, v43
	v_cvt_pk_bf16_f32 v43, v44, v45
	s_waitcnt vmcnt(8)
	v_lshlrev_b32_e32 v74, 16, v206
	v_and_b32_e32 v75, 0xffff0000, v206
	v_lshlrev_b32_e32 v76, 16, v207
	v_and_b32_e32 v77, 0xffff0000, v207
	v_mul_f32_e32 v78, 0xbfb8aa3b, v74
	v_mul_f32_e32 v79, 0xbfb8aa3b, v75
	v_mul_f32_e32 v80, 0xbfb8aa3b, v76
	v_mul_f32_e32 v81, 0xbfb8aa3b, v77
	v_exp_f32_e32 v78, v78
	v_exp_f32_e32 v79, v79
	v_exp_f32_e32 v80, v80
	v_exp_f32_e32 v81, v81
	v_pk_mul_f32 v[46:47], v[46:47], v[74:75]
	v_pk_mul_f32 v[48:49], v[48:49], v[76:77]
	v_add_f32_e32 v78, 1.0, v78
	v_add_f32_e32 v79, 1.0, v79
	v_add_f32_e32 v80, 1.0, v80
	v_add_f32_e32 v81, 1.0, v81
	v_rcp_f32_e32 v78, v78
	v_rcp_f32_e32 v79, v79
	v_rcp_f32_e32 v80, v80
	v_rcp_f32_e32 v81, v81
	v_pk_mul_f32 v[46:47], v[46:47], v[78:79]
	v_pk_mul_f32 v[48:49], v[48:49], v[80:81]
	v_cvt_pk_bf16_f32 v46, v46, v47
	v_cvt_pk_bf16_f32 v47, v48, v49
	s_waitcnt vmcnt(7)
	v_lshlrev_b32_e32 v66, 16, v208
	v_and_b32_e32 v67, 0xffff0000, v208
	v_lshlrev_b32_e32 v68, 16, v209
	v_and_b32_e32 v69, 0xffff0000, v209
	v_mul_f32_e32 v70, 0xbfb8aa3b, v66
	v_mul_f32_e32 v71, 0xbfb8aa3b, v67
	v_mul_f32_e32 v72, 0xbfb8aa3b, v68
	v_mul_f32_e32 v73, 0xbfb8aa3b, v69
	v_exp_f32_e32 v70, v70
	v_exp_f32_e32 v71, v71
	v_exp_f32_e32 v72, v72
	v_exp_f32_e32 v73, v73
	v_pk_mul_f32 v[18:19], v[18:19], v[66:67]
	v_pk_mul_f32 v[20:21], v[20:21], v[68:69]
	v_add_f32_e32 v70, 1.0, v70
	v_add_f32_e32 v71, 1.0, v71
	v_add_f32_e32 v72, 1.0, v72
	v_add_f32_e32 v73, 1.0, v73
	v_rcp_f32_e32 v70, v70
	v_rcp_f32_e32 v71, v71
	v_rcp_f32_e32 v72, v72
	v_rcp_f32_e32 v73, v73
	v_pk_mul_f32 v[18:19], v[18:19], v[70:71]
	v_pk_mul_f32 v[20:21], v[20:21], v[72:73]
	v_cvt_pk_bf16_f32 v18, v18, v19
	v_cvt_pk_bf16_f32 v19, v20, v21
	s_waitcnt vmcnt(6)
	v_lshlrev_b32_e32 v74, 16, v210
	v_and_b32_e32 v75, 0xffff0000, v210
	v_lshlrev_b32_e32 v76, 16, v211
	v_and_b32_e32 v77, 0xffff0000, v211
	v_mul_f32_e32 v78, 0xbfb8aa3b, v74
	v_mul_f32_e32 v79, 0xbfb8aa3b, v75
	v_mul_f32_e32 v80, 0xbfb8aa3b, v76
	v_mul_f32_e32 v81, 0xbfb8aa3b, v77
	v_exp_f32_e32 v78, v78
	v_exp_f32_e32 v79, v79
	v_exp_f32_e32 v80, v80
	v_exp_f32_e32 v81, v81
	v_pk_mul_f32 v[22:23], v[22:23], v[74:75]
	v_pk_mul_f32 v[24:25], v[24:25], v[76:77]
	v_add_f32_e32 v78, 1.0, v78
	v_add_f32_e32 v79, 1.0, v79
	v_add_f32_e32 v80, 1.0, v80
	v_add_f32_e32 v81, 1.0, v81
	v_rcp_f32_e32 v78, v78
	v_rcp_f32_e32 v79, v79
	v_rcp_f32_e32 v80, v80
	v_rcp_f32_e32 v81, v81
	v_pk_mul_f32 v[22:23], v[22:23], v[78:79]
	v_pk_mul_f32 v[24:25], v[24:25], v[80:81]
	v_cvt_pk_bf16_f32 v22, v22, v23
	v_cvt_pk_bf16_f32 v23, v24, v25
	s_waitcnt vmcnt(5)
	v_lshlrev_b32_e32 v66, 16, v212
	v_and_b32_e32 v67, 0xffff0000, v212
	v_lshlrev_b32_e32 v68, 16, v213
	v_and_b32_e32 v69, 0xffff0000, v213
	v_mul_f32_e32 v70, 0xbfb8aa3b, v66
	v_mul_f32_e32 v71, 0xbfb8aa3b, v67
	v_mul_f32_e32 v72, 0xbfb8aa3b, v68
	v_mul_f32_e32 v73, 0xbfb8aa3b, v69
	v_exp_f32_e32 v70, v70
	v_exp_f32_e32 v71, v71
	v_exp_f32_e32 v72, v72
	v_exp_f32_e32 v73, v73
	v_pk_mul_f32 v[26:27], v[26:27], v[66:67]
	v_pk_mul_f32 v[28:29], v[28:29], v[68:69]
	v_add_f32_e32 v70, 1.0, v70
	v_add_f32_e32 v71, 1.0, v71
	v_add_f32_e32 v72, 1.0, v72
	v_add_f32_e32 v73, 1.0, v73
	v_rcp_f32_e32 v70, v70
	v_rcp_f32_e32 v71, v71
	v_rcp_f32_e32 v72, v72
	v_rcp_f32_e32 v73, v73
	v_pk_mul_f32 v[26:27], v[26:27], v[70:71]
	v_pk_mul_f32 v[28:29], v[28:29], v[72:73]
	v_cvt_pk_bf16_f32 v26, v26, v27
	v_cvt_pk_bf16_f32 v27, v28, v29
	s_waitcnt vmcnt(4)
; DI unsigned pk2(float a, float b) { f32x2 v = {a, b}; bf16v2 r = __builtin_convertvector(v, bf16v2); return __builtin_bit_cast(unsigned, r); }
; DI float bf_lo(unsigned u) { return __uint_as_float(u << 16); }
; DI float bf_hi(unsigned u) { return __uint_as_float(u & 0xffff0000u); }
; DI size_t zrowU(int row0, int NT) { return ((size_t)((row0 >> 8) * NT) << 16) + (size_t)((((row0 >> 7) & 1) << 15) | (((row0 >> 5) & 1) << 14) | (((row0 >> 6) & 1) << 11)); }
; DI unsigned zlaneRC(int r5, int col) { return (unsigned)(((col >> 8) << 16) | ((r5 >> 4) << 13) | (((col >> 7) & 1) << 12) | (((col >> 5) & 3) << 9) | (((col >> 3) & 3) << 7) | ((r5 & 15) << 3) | (col & 7)); }
; DI float silu_mul(float o, float g) { return o * g * __builtin_amdgcn_rcpf(1.0f + __builtin_amdgcn_exp2f(g * -1.4426950408889634f)); }
; DI void attnB_item(bf16_t* z, int hh, int qs, LAS bf16_t* vs, int lane) {
;     ...
;     if (!metaq || c < NMETA) {
;         bf16_t* orow = z + zrowU(qrow0, 32) + zlaneRC(c, hh * 128 + 4 * h);
;         const bf16_t* grow = z + zrowU(qrow0, 32) + zlaneRC(c, 6144 + hh * 128 + 4 * h);
; #pragma unroll
;         for (int dt = 0; dt < 4; ++dt)
; #pragma unroll
;             for (int g = 0; g < 4; ++g) {
;                 const int d0 = (dt << 9) | (g << 7);
;                 const u32x2 gv = *(const u32x2*)(grow + d0);
;                 u32x2 o; o.x = pk2(silu_mul(acc[dt][4 * g], bf_lo(gv.x)), silu_mul(acc[dt][4 * g + 1], bf_hi(gv.x)));
;                 o.y = pk2(silu_mul(acc[dt][4 * g + 2], bf_lo(gv.y)), silu_mul(acc[dt][4 * g + 3], bf_hi(gv.y)));
;                 *(u32x2*)(orow + d0) = o;
;             }
;     }
	v_lshlrev_b32_e32 v74, 16, v214
	v_and_b32_e32 v75, 0xffff0000, v214
	v_lshlrev_b32_e32 v76, 16, v215
	v_and_b32_e32 v77, 0xffff0000, v215
	v_mul_f32_e32 v78, 0xbfb8aa3b, v74
	v_mul_f32_e32 v79, 0xbfb8aa3b, v75
	v_mul_f32_e32 v80, 0xbfb8aa3b, v76
	v_mul_f32_e32 v81, 0xbfb8aa3b, v77
	v_exp_f32_e32 v78, v78
	v_exp_f32_e32 v79, v79
	v_exp_f32_e32 v80, v80
	v_exp_f32_e32 v81, v81
	v_pk_mul_f32 v[30:31], v[30:31], v[74:75]
	v_pk_mul_f32 v[32:33], v[32:33], v[76:77]
	v_add_f32_e32 v78, 1.0, v78
	v_add_f32_e32 v79, 1.0, v79
	v_add_f32_e32 v80, 1.0, v80
	v_add_f32_e32 v81, 1.0, v81
	v_rcp_f32_e32 v78, v78
	v_rcp_f32_e32 v79, v79
	v_rcp_f32_e32 v80, v80
	v_rcp_f32_e32 v81, v81
	v_pk_mul_f32 v[30:31], v[30:31], v[78:79]
	v_pk_mul_f32 v[32:33], v[32:33], v[80:81]
	v_cvt_pk_bf16_f32 v30, v30, v31
	v_cvt_pk_bf16_f32 v31, v32, v33
	s_waitcnt vmcnt(3)
	v_lshlrev_b32_e32 v66, 16, v216
	v_and_b32_e32 v67, 0xffff0000, v216
	v_lshlrev_b32_e32 v68, 16, v217
	v_and_b32_e32 v69, 0xffff0000, v217
	v_mul_f32_e32 v70, 0xbfb8aa3b, v66
	v_mul_f32_e32 v71, 0xbfb8aa3b, v67
	v_mul_f32_e32 v72, 0xbfb8aa3b, v68
	v_mul_f32_e32 v73, 0xbfb8aa3b, v69
	v_exp_f32_e32 v70, v70
	v_exp_f32_e32 v71, v71
	v_exp_f32_e32 v72, v72
	v_exp_f32_e32 v73, v73
	v_pk_mul_f32 v[2:3], v[2:3], v[66:67]
	v_pk_mul_f32 v[4:5], v[4:5], v[68:69]
	v_add_f32_e32 v70, 1.0, v70
	v_add_f32_e32 v71, 1.0, v71
	v_add_f32_e32 v72, 1.0, v72
	v_add_f32_e32 v73, 1.0, v73
	v_rcp_f32_e32 v70, v70
	v_rcp_f32_e32 v71, v71
	v_rcp_f32_e32 v72, v72
	v_rcp_f32_e32 v73, v73
	v_pk_mul_f32 v[2:3], v[2:3], v[70:71]
	v_pk_mul_f32 v[4:5], v[4:5], v[72:73]
	v_cvt_pk_bf16_f32 v2, v2, v3
	v_cvt_pk_bf16_f32 v3, v4, v5
	s_waitcnt vmcnt(2)
	v_lshlrev_b32_e32 v74, 16, v218
	v_and_b32_e32 v75, 0xffff0000, v218
	v_lshlrev_b32_e32 v76, 16, v219
	v_and_b32_e32 v77, 0xffff0000, v219
	v_mul_f32_e32 v78, 0xbfb8aa3b, v74
	v_mul_f32_e32 v79, 0xbfb8aa3b, v75
	v_mul_f32_e32 v80, 0xbfb8aa3b, v76
	v_mul_f32_e32 v81, 0xbfb8aa3b, v77
	v_exp_f32_e32 v78, v78
	v_exp_f32_e32 v79, v79
	v_exp_f32_e32 v80, v80
	v_exp_f32_e32 v81, v81
	v_pk_mul_f32 v[6:7], v[6:7], v[74:75]
	v_pk_mul_f32 v[8:9], v[8:9], v[76:77]
	v_add_f32_e32 v78, 1.0, v78
	v_add_f32_e32 v79, 1.0, v79
	v_add_f32_e32 v80, 1.0, v80
	v_add_f32_e32 v81, 1.0, v81
	v_rcp_f32_e32 v78, v78
	v_rcp_f32_e32 v79, v79
	v_rcp_f32_e32 v80, v80
	v_rcp_f32_e32 v81, v81
	v_pk_mul_f32 v[6:7], v[6:7], v[78:79]
	v_pk_mul_f32 v[8:9], v[8:9], v[80:81]
	v_cvt_pk_bf16_f32 v6, v6, v7
	v_cvt_pk_bf16_f32 v7, v8, v9
	s_waitcnt vmcnt(1)
	v_lshlrev_b32_e32 v66, 16, v220
	v_and_b32_e32 v67, 0xffff0000, v220
	v_lshlrev_b32_e32 v68, 16, v221
	v_and_b32_e32 v69, 0xffff0000, v221
	v_mul_f32_e32 v70, 0xbfb8aa3b, v66
	v_mul_f32_e32 v71, 0xbfb8aa3b, v67
	v_mul_f32_e32 v72, 0xbfb8aa3b, v68
	v_mul_f32_e32 v73, 0xbfb8aa3b, v69
	v_exp_f32_e32 v70, v70
	v_exp_f32_e32 v71, v71
	v_exp_f32_e32 v72, v72
	v_exp_f32_e32 v73, v73
	v_pk_mul_f32 v[10:11], v[10:11], v[66:67]
	v_pk_mul_f32 v[12:13], v[12:13], v[68:69]
	v_add_f32_e32 v70, 1.0, v70
	v_add_f32_e32 v71, 1.0, v71
	v_add_f32_e32 v72, 1.0, v72
	v_add_f32_e32 v73, 1.0, v73
	v_rcp_f32_e32 v70, v70
	v_rcp_f32_e32 v71, v71
	v_rcp_f32_e32 v72, v72
	v_rcp_f32_e32 v73, v73
	v_pk_mul_f32 v[10:11], v[10:11], v[70:71]
	v_pk_mul_f32 v[12:13], v[12:13], v[72:73]
	v_cvt_pk_bf16_f32 v10, v10, v11
	v_cvt_pk_bf16_f32 v11, v12, v13
	s_waitcnt vmcnt(0)
	v_lshlrev_b32_e32 v74, 16, v222
	v_and_b32_e32 v75, 0xffff0000, v222
	v_lshlrev_b32_e32 v76, 16, v223
	v_and_b32_e32 v77, 0xffff0000, v223
	v_mul_f32_e32 v78, 0xbfb8aa3b, v74
	v_mul_f32_e32 v79, 0xbfb8aa3b, v75
	v_mul_f32_e32 v80, 0xbfb8aa3b, v76
	v_mul_f32_e32 v81, 0xbfb8aa3b, v77
	v_exp_f32_e32 v78, v78
	v_exp_f32_e32 v79, v79
	v_exp_f32_e32 v80, v80
	v_exp_f32_e32 v81, v81
	v_pk_mul_f32 v[14:15], v[14:15], v[74:75]
	v_pk_mul_f32 v[16:17], v[16:17], v[76:77]
	v_add_f32_e32 v78, 1.0, v78
	v_add_f32_e32 v79, 1.0, v79
	v_add_f32_e32 v80, 1.0, v80
	v_add_f32_e32 v81, 1.0, v81
	v_rcp_f32_e32 v78, v78
	v_rcp_f32_e32 v79, v79
	v_rcp_f32_e32 v80, v80
	v_rcp_f32_e32 v81, v81
	v_pk_mul_f32 v[14:15], v[14:15], v[78:79]
	v_pk_mul_f32 v[16:17], v[16:17], v[80:81]
	v_cvt_pk_bf16_f32 v14, v14, v15
	v_cvt_pk_bf16_f32 v15, v16, v17
	global_store_dwordx2 v[146:147], v[50:51], off
	global_store_dwordx2 v[146:147], v[54:55], off offset:256
	global_store_dwordx2 v[146:147], v[58:59], off offset:512
	global_store_dwordx2 v[146:147], v[62:63], off offset:768
	global_store_dwordx2 v[146:147], v[34:35], off offset:1024
	global_store_dwordx2 v[146:147], v[38:39], off offset:1280
	global_store_dwordx2 v[146:147], v[42:43], off offset:1536
	global_store_dwordx2 v[146:147], v[46:47], off offset:1792
	global_store_dwordx2 v[146:147], v[18:19], off offset:2048
	global_store_dwordx2 v[146:147], v[22:23], off offset:2304
	global_store_dwordx2 v[146:147], v[26:27], off offset:2560
	global_store_dwordx2 v[146:147], v[30:31], off offset:2816
	global_store_dwordx2 v[146:147], v[2:3], off offset:3072
	global_store_dwordx2 v[146:147], v[6:7], off offset:3328
	global_store_dwordx2 v[146:147], v[10:11], off offset:3584
	global_store_dwordx2 v[146:147], v[14:15], off offset:3840
	s_branch .LBB0_130

; DI unsigned pk2(float a, float b) { f32x2 v = {a, b}; bf16v2 r = __builtin_convertvector(v, bf16v2); return __builtin_bit_cast(unsigned, r); }
; DI float bf_lo(unsigned u) { return __uint_as_float(u << 16); }
; DI float bf_hi(unsigned u) { return __uint_as_float(u & 0xffff0000u); }
; DI size_t zrowU(int row0, int NT) { return ((size_t)((row0 >> 8) * NT) << 16) + (size_t)((((row0 >> 7) & 1) << 15) | (((row0 >> 5) & 1) << 14) | (((row0 >> 6) & 1) << 11)); }
; DI unsigned zlaneRC(int r5, int col) { return (unsigned)(((col >> 8) << 16) | ((r5 >> 4) << 13) | (((col >> 7) & 1) << 12) | (((col >> 5) & 3) << 9) | (((col >> 3) & 3) << 7) | ((r5 & 15) << 3) | (col & 7)); }
; DI float silu_mul(float o, float g) { return o * g * __builtin_amdgcn_rcpf(1.0f + __builtin_amdgcn_exp2f(g * -1.4426950408889634f)); }
; DI void attnA_item(bf16_t* z, const float* sinks, int hp, int qs, LAS bf16_t* vs, const LAS float* btab, int lane) {
;     ...
;     if (!metaq || c < NMETA) {
; #pragma unroll
;         for (int u = 0; u < 2; ++u) {
;             const float inv = 1.0f / l[u];
;             bf16_t* orow = z + zrowU(qrow0, 18) + zlaneRC(c, (2 * hp + u) * 64 + 4 * h);
;             const bf16_t* grow = z + zrowU(qrow0, 18) + zlaneRC(c, 2560 + (2 * hp + u) * 64 + 4 * h);
; #pragma unroll
;             for (int dt = 0; dt < 2; ++dt)
; #pragma unroll
;                 for (int g = 0; g < 4; ++g) {
;                     const int d0 = (dt << 9) | (g << 7);
;                     const u32x2 gv = *(const u32x2*)(grow + d0);
;                     u32x2 o; o.x = pk2(silu_mul(acc[u][dt][4 * g] * inv, bf_lo(gv.x)), silu_mul(acc[u][dt][4 * g + 1] * inv, bf_hi(gv.x)));
;                     o.y = pk2(silu_mul(acc[u][dt][4 * g + 2] * inv, bf_lo(gv.y)), silu_mul(acc[u][dt][4 * g + 3] * inv, bf_hi(gv.y)));
;                     *(u32x2*)(orow + d0) = o;
;                 }
;         }
;     }
.LBB0_211:
	v_cmp_gt_u32_e32 vcc, 16, v127
	s_xor_b64 s[4:5], s[68:69], -1
	s_or_b64 s[4:5], s[4:5], vcc
	s_and_saveexec_b64 s[6:7], s[4:5]
	s_xor_b64 s[36:37], exec, s[6:7]
	s_cbranch_execz .LBB0_177
	v_div_scale_f32 v0, s[4:5], v75, v75, 1.0
	v_rcp_f32_e32 v130, v0
	v_and_b32_e32 v134, 4, v125
	v_add_u32_e32 v135, 0xa00, v125
	v_fma_f32 v148, -v0, v130, 1.0
	v_fmac_f32_e32 v130, v148, v130
	v_div_scale_f32 v148, vcc, 1.0, v75, 1.0
	v_mul_f32_e32 v149, v148, v130
	v_fma_f32 v150, -v0, v149, v148
	v_fmac_f32_e32 v149, v150, v130
	v_fma_f32 v0, -v0, v149, v148
	v_div_fmas_f32 v0, v0, v130, v149
	v_div_fixup_f32 v130, v0, v75, 1.0
	v_add_u32_e32 v0, s27, v125
	v_lshlrev_b32_e32 v136, 8, v0
	v_lshlrev_b32_e32 v0, 5, v0
	v_lshlrev_b32_e32 v137, 6, v126
	v_and_b32_e32 v136, 0xffff0000, v136
	v_and_b32_e32 v0, 0x1000, v0
	v_and_b32_e32 v146, 0x780, v137
	v_or3_b32 v0, v0, v136, v146
	v_or3_b32 v0, v0, v134, v124
	v_lshl_add_u64 v[138:139], v[0:1], 1, s[0:1]
	v_add_u32_e32 v0, s27, v135
	v_lshlrev_b32_e32 v147, 8, v0
	v_lshlrev_b32_e32 v0, 5, v0
	v_and_b32_e32 v147, 0xffff0000, v147
	v_and_b32_e32 v0, 0x1000, v0
	v_or3_b32 v0, v0, v147, v146
	v_or3_b32 v0, v0, v134, v124
	v_lshl_add_u64 v[140:141], v[0:1], 1, s[0:1]
	global_load_dwordx2 v[178:179], v[140:141], off
	global_load_dwordx2 v[180:181], v[140:141], off offset:256
	global_load_dwordx2 v[182:183], v[140:141], off offset:512
	global_load_dwordx2 v[184:185], v[140:141], off offset:768
	global_load_dwordx2 v[186:187], v[140:141], off offset:1024
	global_load_dwordx2 v[188:189], v[140:141], off offset:1280
	global_load_dwordx2 v[190:191], v[140:141], off offset:1536
	global_load_dwordx2 v[192:193], v[140:141], off offset:1792
	v_div_scale_f32 v0, s[4:5], v74, v74, 1.0
	s_or_b32 s4, s27, 64
	v_rcp_f32_e32 v132, v0
	s_nop 0
	v_fma_f32 v148, -v0, v132, 1.0
	v_fmac_f32_e32 v132, v148, v132
	v_div_scale_f32 v148, vcc, 1.0, v74, 1.0
	v_mul_f32_e32 v149, v148, v132
	v_fma_f32 v150, -v0, v149, v148
	v_fmac_f32_e32 v149, v150, v132
	v_fma_f32 v0, -v0, v149, v148
	v_div_fmas_f32 v0, v0, v132, v149
	v_div_fixup_f32 v132, v0, v74, 1.0
	v_add_u32_e32 v0, s4, v125
	v_lshlrev_b32_e32 v136, 8, v0
	v_lshlrev_b32_e32 v137, 5, v0
	v_lshlrev_b32_e32 v0, 4, v0
	v_and_b32_e32 v136, 0xffff0000, v136
	v_and_b32_e32 v137, 0x1000, v137
	v_and_b32_e32 v0, 0x780, v0
	v_or3_b32 v0, v137, v136, v0
	v_or3_b32 v0, v0, v134, v124
	v_lshl_add_u64 v[142:143], v[0:1], 1, s[0:1]
	v_add_u32_e32 v0, s4, v135
	v_lshlrev_b32_e32 v136, 8, v0
	v_lshlrev_b32_e32 v147, 5, v0
	v_lshlrev_b32_e32 v0, 4, v0
	v_and_b32_e32 v136, 0xffff0000, v136
	v_and_b32_e32 v147, 0x1000, v147
	v_and_b32_e32 v0, 0x780, v0
	v_or3_b32 v0, v147, v136, v0
	v_or3_b32 v0, v0, v134, v124
	v_lshl_add_u64 v[144:145], v[0:1], 1, s[0:1]
	global_load_dwordx2 v[194:195], v[144:145], off
	global_load_dwordx2 v[196:197], v[144:145], off offset:256
	global_load_dwordx2 v[198:199], v[144:145], off offset:512
	global_load_dwordx2 v[200:201], v[144:145], off offset:768
	global_load_dwordx2 v[202:203], v[144:145], off offset:1024
	global_load_dwordx2 v[204:205], v[144:145], off offset:1280
	global_load_dwordx2 v[206:207], v[144:145], off offset:1536
	global_load_dwordx2 v[208:209], v[144:145], off offset:1792
	v_pk_mul_f32 v[50:51], v[130:131], v[50:51] op_sel_hi:[0,1]
	v_pk_mul_f32 v[52:53], v[130:131], v[52:53] op_sel_hi:[0,1]
	v_pk_mul_f32 v[54:55], v[130:131], v[54:55] op_sel_hi:[0,1]
	v_pk_mul_f32 v[56:57], v[130:131], v[56:57] op_sel_hi:[0,1]
	v_pk_mul_f32 v[58:59], v[130:131], v[58:59] op_sel_hi:[0,1]
	v_pk_mul_f32 v[60:61], v[130:131], v[60:61] op_sel_hi:[0,1]
	v_pk_mul_f32 v[62:63], v[130:131], v[62:63] op_sel_hi:[0,1]
	v_pk_mul_f32 v[64:65], v[130:131], v[64:65] op_sel_hi:[0,1]
	v_pk_mul_f32 v[34:35], v[130:131], v[34:35] op_sel_hi:[0,1]
	v_pk_mul_f32 v[36:37], v[130:131], v[36:37] op_sel_hi:[0,1]
	v_pk_mul_f32 v[38:39], v[130:131], v[38:39] op_sel_hi:[0,1]
	v_pk_mul_f32 v[40:41], v[130:131], v[40:41] op_sel_hi:[0,1]
	v_pk_mul_f32 v[42:43], v[130:131], v[42:43] op_sel_hi:[0,1]
	v_pk_mul_f32 v[44:45], v[130:131], v[44:45] op_sel_hi:[0,1]
	v_pk_mul_f32 v[46:47], v[130:131], v[46:47] op_sel_hi:[0,1]
	v_pk_mul_f32 v[48:49], v[130:131], v[48:49] op_sel_hi:[0,1]
	v_pk_mul_f32 v[18:19], v[132:133], v[18:19] op_sel_hi:[0,1]
	v_pk_mul_f32 v[20:21], v[132:133], v[20:21] op_sel_hi:[0,1]
	v_pk_mul_f32 v[22:23], v[132:133], v[22:23] op_sel_hi:[0,1]
	v_pk_mul_f32 v[24:25], v[132:133], v[24:25] op_sel_hi:[0,1]
	v_pk_mul_f32 v[26:27], v[132:133], v[26:27] op_sel_hi:[0,1]
	v_pk_mul_f32 v[28:29], v[132:133], v[28:29] op_sel_hi:[0,1]
	v_pk_mul_f32 v[30:31], v[132:133], v[30:31] op_sel_hi:[0,1]
	v_pk_mul_f32 v[32:33], v[132:133], v[32:33] op_sel_hi:[0,1]
	v_pk_mul_f32 v[2:3], v[132:133], v[2:3] op_sel_hi:[0,1]
	v_pk_mul_f32 v[4:5], v[132:133], v[4:5] op_sel_hi:[0,1]
	v_pk_mul_f32 v[6:7], v[132:133], v[6:7] op_sel_hi:[0,1]
	v_pk_mul_f32 v[8:9], v[132:133], v[8:9] op_sel_hi:[0,1]
	v_pk_mul_f32 v[10:11], v[132:133], v[10:11] op_sel_hi:[0,1]
	v_pk_mul_f32 v[12:13], v[132:133], v[12:13] op_sel_hi:[0,1]
	v_pk_mul_f32 v[14:15], v[132:133], v[14:15] op_sel_hi:[0,1]
	v_pk_mul_f32 v[16:17], v[132:133], v[16:17] op_sel_hi:[0,1]
	s_waitcnt vmcnt(15)
	v_lshlrev_b32_e32 v210, 16, v178
	v_and_b32_e32 v211, 0xffff0000, v178
	v_lshlrev_b32_e32 v212, 16, v179
	v_and_b32_e32 v213, 0xffff0000, v179
	v_mul_f32_e32 v214, 0xbfb8aa3b, v210
	v_mul_f32_e32 v215, 0xbfb8aa3b, v211
	v_mul_f32_e32 v216, 0xbfb8aa3b, v212
	v_mul_f32_e32 v217, 0xbfb8aa3b, v213
	v_exp_f32_e32 v214, v214
	v_exp_f32_e32 v215, v215
	v_exp_f32_e32 v216, v216
	v_exp_f32_e32 v217, v217
	v_pk_mul_f32 v[50:51], v[50:51], v[210:211]
	v_pk_mul_f32 v[52:53], v[52:53], v[212:213]
	v_add_f32_e32 v214, 1.0, v214
	v_add_f32_e32 v215, 1.0, v215
	v_add_f32_e32 v216, 1.0, v216
	v_add_f32_e32 v217, 1.0, v217
	v_rcp_f32_e32 v214, v214
	v_rcp_f32_e32 v215, v215
	v_rcp_f32_e32 v216, v216
	v_rcp_f32_e32 v217, v217
	v_pk_mul_f32 v[50:51], v[50:51], v[214:215]
	v_pk_mul_f32 v[52:53], v[52:53], v[216:217]
	v_cvt_pk_bf16_f32 v50, v50, v51
	v_cvt_pk_bf16_f32 v51, v52, v53
	s_waitcnt vmcnt(14)
; DI unsigned pk2(float a, float b) { f32x2 v = {a, b}; bf16v2 r = __builtin_convertvector(v, bf16v2); return __builtin_bit_cast(unsigned, r); }
; DI float bf_lo(unsigned u) { return __uint_as_float(u << 16); }
; DI float bf_hi(unsigned u) { return __uint_as_float(u & 0xffff0000u); }
; DI size_t zrowU(int row0, int NT) { return ((size_t)((row0 >> 8) * NT) << 16) + (size_t)((((row0 >> 7) & 1) << 15) | (((row0 >> 5) & 1) << 14) | (((row0 >> 6) & 1) << 11)); }
; DI unsigned zlaneRC(int r5, int col) { return (unsigned)(((col >> 8) << 16) | ((r5 >> 4) << 13) | (((col >> 7) & 1) << 12) | (((col >> 5) & 3) << 9) | (((col >> 3) & 3) << 7) | ((r5 & 15) << 3) | (col & 7)); }
; DI float silu_mul(float o, float g) { return o * g * __builtin_amdgcn_rcpf(1.0f + __builtin_amdgcn_exp2f(g * -1.4426950408889634f)); }
; DI void attnA_item(bf16_t* z, const float* sinks, int hp, int qs, LAS bf16_t* vs, const LAS float* btab, int lane) {
;     ...
;     if (!metaq || c < NMETA) {
; #pragma unroll
;         for (int u = 0; u < 2; ++u) {
;             const float inv = 1.0f / l[u];
;             bf16_t* orow = z + zrowU(qrow0, 18) + zlaneRC(c, (2 * hp + u) * 64 + 4 * h);
;             const bf16_t* grow = z + zrowU(qrow0, 18) + zlaneRC(c, 2560 + (2 * hp + u) * 64 + 4 * h);
; #pragma unroll
;             for (int dt = 0; dt < 2; ++dt)
; #pragma unroll
;                 for (int g = 0; g < 4; ++g) {
;                     const int d0 = (dt << 9) | (g << 7);
;                     const u32x2 gv = *(const u32x2*)(grow + d0);
;                     u32x2 o; o.x = pk2(silu_mul(acc[u][dt][4 * g] * inv, bf_lo(gv.x)), silu_mul(acc[u][dt][4 * g + 1] * inv, bf_hi(gv.x)));
;                     o.y = pk2(silu_mul(acc[u][dt][4 * g + 2] * inv, bf_lo(gv.y)), silu_mul(acc[u][dt][4 * g + 3] * inv, bf_hi(gv.y)));
;                     *(u32x2*)(orow + d0) = o;
;                 }
;         }
;     }
	v_lshlrev_b32_e32 v218, 16, v180
	v_and_b32_e32 v219, 0xffff0000, v180
	v_lshlrev_b32_e32 v220, 16, v181
	v_and_b32_e32 v221, 0xffff0000, v181
	v_mul_f32_e32 v222, 0xbfb8aa3b, v218
	v_mul_f32_e32 v223, 0xbfb8aa3b, v219
	v_mul_f32_e32 v224, 0xbfb8aa3b, v220
	v_mul_f32_e32 v225, 0xbfb8aa3b, v221
	v_exp_f32_e32 v222, v222
	v_exp_f32_e32 v223, v223
	v_exp_f32_e32 v224, v224
	v_exp_f32_e32 v225, v225
	v_pk_mul_f32 v[54:55], v[54:55], v[218:219]
	v_pk_mul_f32 v[56:57], v[56:57], v[220:221]
	v_add_f32_e32 v222, 1.0, v222
	v_add_f32_e32 v223, 1.0, v223
	v_add_f32_e32 v224, 1.0, v224
	v_add_f32_e32 v225, 1.0, v225
	v_rcp_f32_e32 v222, v222
	v_rcp_f32_e32 v223, v223
	v_rcp_f32_e32 v224, v224
	v_rcp_f32_e32 v225, v225
	v_pk_mul_f32 v[54:55], v[54:55], v[222:223]
	v_pk_mul_f32 v[56:57], v[56:57], v[224:225]
	v_cvt_pk_bf16_f32 v54, v54, v55
	v_cvt_pk_bf16_f32 v55, v56, v57
	s_waitcnt vmcnt(13)
	v_lshlrev_b32_e32 v210, 16, v182
	v_and_b32_e32 v211, 0xffff0000, v182
	v_lshlrev_b32_e32 v212, 16, v183
	v_and_b32_e32 v213, 0xffff0000, v183
	v_mul_f32_e32 v214, 0xbfb8aa3b, v210
	v_mul_f32_e32 v215, 0xbfb8aa3b, v211
	v_mul_f32_e32 v216, 0xbfb8aa3b, v212
	v_mul_f32_e32 v217, 0xbfb8aa3b, v213
	v_exp_f32_e32 v214, v214
	v_exp_f32_e32 v215, v215
	v_exp_f32_e32 v216, v216
	v_exp_f32_e32 v217, v217
	v_pk_mul_f32 v[58:59], v[58:59], v[210:211]
	v_pk_mul_f32 v[60:61], v[60:61], v[212:213]
	v_add_f32_e32 v214, 1.0, v214
	v_add_f32_e32 v215, 1.0, v215
	v_add_f32_e32 v216, 1.0, v216
	v_add_f32_e32 v217, 1.0, v217
	v_rcp_f32_e32 v214, v214
	v_rcp_f32_e32 v215, v215
	v_rcp_f32_e32 v216, v216
	v_rcp_f32_e32 v217, v217
	v_pk_mul_f32 v[58:59], v[58:59], v[214:215]
	v_pk_mul_f32 v[60:61], v[60:61], v[216:217]
	v_cvt_pk_bf16_f32 v58, v58, v59
	v_cvt_pk_bf16_f32 v59, v60, v61
	s_waitcnt vmcnt(12)
	v_lshlrev_b32_e32 v218, 16, v184
	v_and_b32_e32 v219, 0xffff0000, v184
	v_lshlrev_b32_e32 v220, 16, v185
	v_and_b32_e32 v221, 0xffff0000, v185
	v_mul_f32_e32 v222, 0xbfb8aa3b, v218
	v_mul_f32_e32 v223, 0xbfb8aa3b, v219
	v_mul_f32_e32 v224, 0xbfb8aa3b, v220
	v_mul_f32_e32 v225, 0xbfb8aa3b, v221
	v_exp_f32_e32 v222, v222
	v_exp_f32_e32 v223, v223
	v_exp_f32_e32 v224, v224
	v_exp_f32_e32 v225, v225
	v_pk_mul_f32 v[62:63], v[62:63], v[218:219]
	v_pk_mul_f32 v[64:65], v[64:65], v[220:221]
	v_add_f32_e32 v222, 1.0, v222
	v_add_f32_e32 v223, 1.0, v223
	v_add_f32_e32 v224, 1.0, v224
	v_add_f32_e32 v225, 1.0, v225
	v_rcp_f32_e32 v222, v222
	v_rcp_f32_e32 v223, v223
	v_rcp_f32_e32 v224, v224
	v_rcp_f32_e32 v225, v225
	v_pk_mul_f32 v[62:63], v[62:63], v[222:223]
	v_pk_mul_f32 v[64:65], v[64:65], v[224:225]
	v_cvt_pk_bf16_f32 v62, v62, v63
	v_cvt_pk_bf16_f32 v63, v64, v65
	s_waitcnt vmcnt(11)
	v_lshlrev_b32_e32 v210, 16, v186
	v_and_b32_e32 v211, 0xffff0000, v186
	v_lshlrev_b32_e32 v212, 16, v187
	v_and_b32_e32 v213, 0xffff0000, v187
	v_mul_f32_e32 v214, 0xbfb8aa3b, v210
	v_mul_f32_e32 v215, 0xbfb8aa3b, v211
	v_mul_f32_e32 v216, 0xbfb8aa3b, v212
	v_mul_f32_e32 v217, 0xbfb8aa3b, v213
	v_exp_f32_e32 v214, v214
	v_exp_f32_e32 v215, v215
	v_exp_f32_e32 v216, v216
	v_exp_f32_e32 v217, v217
	v_pk_mul_f32 v[34:35], v[34:35], v[210:211]
	v_pk_mul_f32 v[36:37], v[36:37], v[212:213]
	v_add_f32_e32 v214, 1.0, v214
	v_add_f32_e32 v215, 1.0, v215
	v_add_f32_e32 v216, 1.0, v216
	v_add_f32_e32 v217, 1.0, v217
	v_rcp_f32_e32 v214, v214
	v_rcp_f32_e32 v215, v215
	v_rcp_f32_e32 v216, v216
	v_rcp_f32_e32 v217, v217
	v_pk_mul_f32 v[34:35], v[34:35], v[214:215]
	v_pk_mul_f32 v[36:37], v[36:37], v[216:217]
	v_cvt_pk_bf16_f32 v34, v34, v35
	v_cvt_pk_bf16_f32 v35, v36, v37
	s_waitcnt vmcnt(10)
	v_lshlrev_b32_e32 v218, 16, v188
	v_and_b32_e32 v219, 0xffff0000, v188
	v_lshlrev_b32_e32 v220, 16, v189
	v_and_b32_e32 v221, 0xffff0000, v189
	v_mul_f32_e32 v222, 0xbfb8aa3b, v218
	v_mul_f32_e32 v223, 0xbfb8aa3b, v219
	v_mul_f32_e32 v224, 0xbfb8aa3b, v220
	v_mul_f32_e32 v225, 0xbfb8aa3b, v221
	v_exp_f32_e32 v222, v222
	v_exp_f32_e32 v223, v223
	v_exp_f32_e32 v224, v224
	v_exp_f32_e32 v225, v225
	v_pk_mul_f32 v[38:39], v[38:39], v[218:219]
	v_pk_mul_f32 v[40:41], v[40:41], v[220:221]
	v_add_f32_e32 v222, 1.0, v222
	v_add_f32_e32 v223, 1.0, v223
	v_add_f32_e32 v224, 1.0, v224
	v_add_f32_e32 v225, 1.0, v225
	v_rcp_f32_e32 v222, v222
	v_rcp_f32_e32 v223, v223
	v_rcp_f32_e32 v224, v224
	v_rcp_f32_e32 v225, v225
	v_pk_mul_f32 v[38:39], v[38:39], v[222:223]
	v_pk_mul_f32 v[40:41], v[40:41], v[224:225]
	v_cvt_pk_bf16_f32 v38, v38, v39
	v_cvt_pk_bf16_f32 v39, v40, v41
	s_waitcnt vmcnt(9)
	v_lshlrev_b32_e32 v210, 16, v190
	v_and_b32_e32 v211, 0xffff0000, v190
	v_lshlrev_b32_e32 v212, 16, v191
	v_and_b32_e32 v213, 0xffff0000, v191
	v_mul_f32_e32 v214, 0xbfb8aa3b, v210
	v_mul_f32_e32 v215, 0xbfb8aa3b, v211
	v_mul_f32_e32 v216, 0xbfb8aa3b, v212
	v_mul_f32_e32 v217, 0xbfb8aa3b, v213
	v_exp_f32_e32 v214, v214
	v_exp_f32_e32 v215, v215
	v_exp_f32_e32 v216, v216
	v_exp_f32_e32 v217, v217
	v_pk_mul_f32 v[42:43], v[42:43], v[210:211]
	v_pk_mul_f32 v[44:45], v[44:45], v[212:213]
	v_add_f32_e32 v214, 1.0, v214
	v_add_f32_e32 v215, 1.0, v215
	v_add_f32_e32 v216, 1.0, v216
	v_add_f32_e32 v217, 1.0, v217
	v_rcp_f32_e32 v214, v214
	v_rcp_f32_e32 v215, v215
	v_rcp_f32_e32 v216, v216
	v_rcp_f32_e32 v217, v217
	v_pk_mul_f32 v[42:43], v[42:43], v[214:215]
	v_pk_mul_f32 v[44:45], v[44:45], v[216:217]
	v_cvt_pk_bf16_f32 v42, v42, v43
	v_cvt_pk_bf16_f32 v43, v44, v45
	s_waitcnt vmcnt(8)
; DI unsigned pk2(float a, float b) { f32x2 v = {a, b}; bf16v2 r = __builtin_convertvector(v, bf16v2); return __builtin_bit_cast(unsigned, r); }
; DI float bf_lo(unsigned u) { return __uint_as_float(u << 16); }
; DI float bf_hi(unsigned u) { return __uint_as_float(u & 0xffff0000u); }
; DI size_t zrowU(int row0, int NT) { return ((size_t)((row0 >> 8) * NT) << 16) + (size_t)((((row0 >> 7) & 1) << 15) | (((row0 >> 5) & 1) << 14) | (((row0 >> 6) & 1) << 11)); }
; DI unsigned zlaneRC(int r5, int col) { return (unsigned)(((col >> 8) << 16) | ((r5 >> 4) << 13) | (((col >> 7) & 1) << 12) | (((col >> 5) & 3) << 9) | (((col >> 3) & 3) << 7) | ((r5 & 15) << 3) | (col & 7)); }
; DI float silu_mul(float o, float g) { return o * g * __builtin_amdgcn_rcpf(1.0f + __builtin_amdgcn_exp2f(g * -1.4426950408889634f)); }
; DI void attnA_item(bf16_t* z, const float* sinks, int hp, int qs, LAS bf16_t* vs, const LAS float* btab, int lane) {
;     ...
;     if (!metaq || c < NMETA) {
; #pragma unroll
;         for (int u = 0; u < 2; ++u) {
;             const float inv = 1.0f / l[u];
;             bf16_t* orow = z + zrowU(qrow0, 18) + zlaneRC(c, (2 * hp + u) * 64 + 4 * h);
;             const bf16_t* grow = z + zrowU(qrow0, 18) + zlaneRC(c, 2560 + (2 * hp + u) * 64 + 4 * h);
; #pragma unroll
;             for (int dt = 0; dt < 2; ++dt)
; #pragma unroll
;                 for (int g = 0; g < 4; ++g) {
;                     const int d0 = (dt << 9) | (g << 7);
;                     const u32x2 gv = *(const u32x2*)(grow + d0);
;                     u32x2 o; o.x = pk2(silu_mul(acc[u][dt][4 * g] * inv, bf_lo(gv.x)), silu_mul(acc[u][dt][4 * g + 1] * inv, bf_hi(gv.x)));
;                     o.y = pk2(silu_mul(acc[u][dt][4 * g + 2] * inv, bf_lo(gv.y)), silu_mul(acc[u][dt][4 * g + 3] * inv, bf_hi(gv.y)));
;                     *(u32x2*)(orow + d0) = o;
;                 }
;         }
;     }
	v_lshlrev_b32_e32 v218, 16, v192
	v_and_b32_e32 v219, 0xffff0000, v192
	v_lshlrev_b32_e32 v220, 16, v193
	v_and_b32_e32 v221, 0xffff0000, v193
	v_mul_f32_e32 v222, 0xbfb8aa3b, v218
	v_mul_f32_e32 v223, 0xbfb8aa3b, v219
	v_mul_f32_e32 v224, 0xbfb8aa3b, v220
	v_mul_f32_e32 v225, 0xbfb8aa3b, v221
	v_exp_f32_e32 v222, v222
	v_exp_f32_e32 v223, v223
	v_exp_f32_e32 v224, v224
	v_exp_f32_e32 v225, v225
	v_pk_mul_f32 v[46:47], v[46:47], v[218:219]
	v_pk_mul_f32 v[48:49], v[48:49], v[220:221]
	v_add_f32_e32 v222, 1.0, v222
	v_add_f32_e32 v223, 1.0, v223
	v_add_f32_e32 v224, 1.0, v224
	v_add_f32_e32 v225, 1.0, v225
	v_rcp_f32_e32 v222, v222
	v_rcp_f32_e32 v223, v223
	v_rcp_f32_e32 v224, v224
	v_rcp_f32_e32 v225, v225
	v_pk_mul_f32 v[46:47], v[46:47], v[222:223]
	v_pk_mul_f32 v[48:49], v[48:49], v[224:225]
	v_cvt_pk_bf16_f32 v46, v46, v47
	v_cvt_pk_bf16_f32 v47, v48, v49
	s_waitcnt vmcnt(7)
	v_lshlrev_b32_e32 v210, 16, v194
	v_and_b32_e32 v211, 0xffff0000, v194
	v_lshlrev_b32_e32 v212, 16, v195
	v_and_b32_e32 v213, 0xffff0000, v195
	v_mul_f32_e32 v214, 0xbfb8aa3b, v210
	v_mul_f32_e32 v215, 0xbfb8aa3b, v211
	v_mul_f32_e32 v216, 0xbfb8aa3b, v212
	v_mul_f32_e32 v217, 0xbfb8aa3b, v213
	v_exp_f32_e32 v214, v214
	v_exp_f32_e32 v215, v215
	v_exp_f32_e32 v216, v216
	v_exp_f32_e32 v217, v217
	v_pk_mul_f32 v[18:19], v[18:19], v[210:211]
	v_pk_mul_f32 v[20:21], v[20:21], v[212:213]
	v_add_f32_e32 v214, 1.0, v214
	v_add_f32_e32 v215, 1.0, v215
	v_add_f32_e32 v216, 1.0, v216
	v_add_f32_e32 v217, 1.0, v217
	v_rcp_f32_e32 v214, v214
	v_rcp_f32_e32 v215, v215
	v_rcp_f32_e32 v216, v216
	v_rcp_f32_e32 v217, v217
	v_pk_mul_f32 v[18:19], v[18:19], v[214:215]
	v_pk_mul_f32 v[20:21], v[20:21], v[216:217]
	v_cvt_pk_bf16_f32 v18, v18, v19
	v_cvt_pk_bf16_f32 v19, v20, v21
	s_waitcnt vmcnt(6)
	v_lshlrev_b32_e32 v218, 16, v196
	v_and_b32_e32 v219, 0xffff0000, v196
	v_lshlrev_b32_e32 v220, 16, v197
	v_and_b32_e32 v221, 0xffff0000, v197
	v_mul_f32_e32 v222, 0xbfb8aa3b, v218
	v_mul_f32_e32 v223, 0xbfb8aa3b, v219
	v_mul_f32_e32 v224, 0xbfb8aa3b, v220
	v_mul_f32_e32 v225, 0xbfb8aa3b, v221
	v_exp_f32_e32 v222, v222
	v_exp_f32_e32 v223, v223
	v_exp_f32_e32 v224, v224
	v_exp_f32_e32 v225, v225
	v_pk_mul_f32 v[22:23], v[22:23], v[218:219]
	v_pk_mul_f32 v[24:25], v[24:25], v[220:221]
	v_add_f32_e32 v222, 1.0, v222
	v_add_f32_e32 v223, 1.0, v223
	v_add_f32_e32 v224, 1.0, v224
	v_add_f32_e32 v225, 1.0, v225
	v_rcp_f32_e32 v222, v222
	v_rcp_f32_e32 v223, v223
	v_rcp_f32_e32 v224, v224
	v_rcp_f32_e32 v225, v225
	v_pk_mul_f32 v[22:23], v[22:23], v[222:223]
	v_pk_mul_f32 v[24:25], v[24:25], v[224:225]
	v_cvt_pk_bf16_f32 v22, v22, v23
	v_cvt_pk_bf16_f32 v23, v24, v25
	s_waitcnt vmcnt(5)
	v_lshlrev_b32_e32 v210, 16, v198
	v_and_b32_e32 v211, 0xffff0000, v198
	v_lshlrev_b32_e32 v212, 16, v199
	v_and_b32_e32 v213, 0xffff0000, v199
	v_mul_f32_e32 v214, 0xbfb8aa3b, v210
	v_mul_f32_e32 v215, 0xbfb8aa3b, v211
	v_mul_f32_e32 v216, 0xbfb8aa3b, v212
	v_mul_f32_e32 v217, 0xbfb8aa3b, v213
	v_exp_f32_e32 v214, v214
	v_exp_f32_e32 v215, v215
	v_exp_f32_e32 v216, v216
	v_exp_f32_e32 v217, v217
	v_pk_mul_f32 v[26:27], v[26:27], v[210:211]
	v_pk_mul_f32 v[28:29], v[28:29], v[212:213]
	v_add_f32_e32 v214, 1.0, v214
	v_add_f32_e32 v215, 1.0, v215
	v_add_f32_e32 v216, 1.0, v216
	v_add_f32_e32 v217, 1.0, v217
	v_rcp_f32_e32 v214, v214
	v_rcp_f32_e32 v215, v215
	v_rcp_f32_e32 v216, v216
	v_rcp_f32_e32 v217, v217
	v_pk_mul_f32 v[26:27], v[26:27], v[214:215]
	v_pk_mul_f32 v[28:29], v[28:29], v[216:217]
	v_cvt_pk_bf16_f32 v26, v26, v27
	v_cvt_pk_bf16_f32 v27, v28, v29
	s_waitcnt vmcnt(4)
	v_lshlrev_b32_e32 v218, 16, v200
	v_and_b32_e32 v219, 0xffff0000, v200
	v_lshlrev_b32_e32 v220, 16, v201
	v_and_b32_e32 v221, 0xffff0000, v201
	v_mul_f32_e32 v222, 0xbfb8aa3b, v218
	v_mul_f32_e32 v223, 0xbfb8aa3b, v219
	v_mul_f32_e32 v224, 0xbfb8aa3b, v220
	v_mul_f32_e32 v225, 0xbfb8aa3b, v221
	v_exp_f32_e32 v222, v222
	v_exp_f32_e32 v223, v223
	v_exp_f32_e32 v224, v224
	v_exp_f32_e32 v225, v225
	v_pk_mul_f32 v[30:31], v[30:31], v[218:219]
	v_pk_mul_f32 v[32:33], v[32:33], v[220:221]
	v_add_f32_e32 v222, 1.0, v222
	v_add_f32_e32 v223, 1.0, v223
	v_add_f32_e32 v224, 1.0, v224
	v_add_f32_e32 v225, 1.0, v225
	v_rcp_f32_e32 v222, v222
	v_rcp_f32_e32 v223, v223
	v_rcp_f32_e32 v224, v224
	v_rcp_f32_e32 v225, v225
	v_pk_mul_f32 v[30:31], v[30:31], v[222:223]
	v_pk_mul_f32 v[32:33], v[32:33], v[224:225]
	v_cvt_pk_bf16_f32 v30, v30, v31
	v_cvt_pk_bf16_f32 v31, v32, v33
	s_waitcnt vmcnt(3)
; DI unsigned pk2(float a, float b) { f32x2 v = {a, b}; bf16v2 r = __builtin_convertvector(v, bf16v2); return __builtin_bit_cast(unsigned, r); }
; DI float bf_lo(unsigned u) { return __uint_as_float(u << 16); }
; DI float bf_hi(unsigned u) { return __uint_as_float(u & 0xffff0000u); }
; DI size_t zrowU(int row0, int NT) { return ((size_t)((row0 >> 8) * NT) << 16) + (size_t)((((row0 >> 7) & 1) << 15) | (((row0 >> 5) & 1) << 14) | (((row0 >> 6) & 1) << 11)); }
; DI unsigned zlaneRC(int r5, int col) { return (unsigned)(((col >> 8) << 16) | ((r5 >> 4) << 13) | (((col >> 7) & 1) << 12) | (((col >> 5) & 3) << 9) | (((col >> 3) & 3) << 7) | ((r5 & 15) << 3) | (col & 7)); }
; DI float silu_mul(float o, float g) { return o * g * __builtin_amdgcn_rcpf(1.0f + __builtin_amdgcn_exp2f(g * -1.4426950408889634f)); }
; DI void attnA_item(bf16_t* z, const float* sinks, int hp, int qs, LAS bf16_t* vs, const LAS float* btab, int lane) {
;     ...
;     if (!metaq || c < NMETA) {
; #pragma unroll
;         for (int u = 0; u < 2; ++u) {
;             const float inv = 1.0f / l[u];
;             bf16_t* orow = z + zrowU(qrow0, 18) + zlaneRC(c, (2 * hp + u) * 64 + 4 * h);
;             const bf16_t* grow = z + zrowU(qrow0, 18) + zlaneRC(c, 2560 + (2 * hp + u) * 64 + 4 * h);
; #pragma unroll
;             for (int dt = 0; dt < 2; ++dt)
; #pragma unroll
;                 for (int g = 0; g < 4; ++g) {
;                     const int d0 = (dt << 9) | (g << 7);
;                     const u32x2 gv = *(const u32x2*)(grow + d0);
;                     u32x2 o; o.x = pk2(silu_mul(acc[u][dt][4 * g] * inv, bf_lo(gv.x)), silu_mul(acc[u][dt][4 * g + 1] * inv, bf_hi(gv.x)));
;                     o.y = pk2(silu_mul(acc[u][dt][4 * g + 2] * inv, bf_lo(gv.y)), silu_mul(acc[u][dt][4 * g + 3] * inv, bf_hi(gv.y)));
;                     *(u32x2*)(orow + d0) = o;
;                 }
;         }
;     }
	v_lshlrev_b32_e32 v210, 16, v202
	v_and_b32_e32 v211, 0xffff0000, v202
	v_lshlrev_b32_e32 v212, 16, v203
	v_and_b32_e32 v213, 0xffff0000, v203
	v_mul_f32_e32 v214, 0xbfb8aa3b, v210
	v_mul_f32_e32 v215, 0xbfb8aa3b, v211
	v_mul_f32_e32 v216, 0xbfb8aa3b, v212
	v_mul_f32_e32 v217, 0xbfb8aa3b, v213
	v_exp_f32_e32 v214, v214
	v_exp_f32_e32 v215, v215
	v_exp_f32_e32 v216, v216
	v_exp_f32_e32 v217, v217
	v_pk_mul_f32 v[2:3], v[2:3], v[210:211]
	v_pk_mul_f32 v[4:5], v[4:5], v[212:213]
	v_add_f32_e32 v214, 1.0, v214
	v_add_f32_e32 v215, 1.0, v215
	v_add_f32_e32 v216, 1.0, v216
	v_add_f32_e32 v217, 1.0, v217
	v_rcp_f32_e32 v214, v214
	v_rcp_f32_e32 v215, v215
	v_rcp_f32_e32 v216, v216
	v_rcp_f32_e32 v217, v217
	v_pk_mul_f32 v[2:3], v[2:3], v[214:215]
	v_pk_mul_f32 v[4:5], v[4:5], v[216:217]
	v_cvt_pk_bf16_f32 v2, v2, v3
	v_cvt_pk_bf16_f32 v3, v4, v5
	s_waitcnt vmcnt(2)
	v_lshlrev_b32_e32 v218, 16, v204
	v_and_b32_e32 v219, 0xffff0000, v204
	v_lshlrev_b32_e32 v220, 16, v205
	v_and_b32_e32 v221, 0xffff0000, v205
	v_mul_f32_e32 v222, 0xbfb8aa3b, v218
	v_mul_f32_e32 v223, 0xbfb8aa3b, v219
	v_mul_f32_e32 v224, 0xbfb8aa3b, v220
	v_mul_f32_e32 v225, 0xbfb8aa3b, v221
	v_exp_f32_e32 v222, v222
	v_exp_f32_e32 v223, v223
	v_exp_f32_e32 v224, v224
	v_exp_f32_e32 v225, v225
	v_pk_mul_f32 v[6:7], v[6:7], v[218:219]
	v_pk_mul_f32 v[8:9], v[8:9], v[220:221]
	v_add_f32_e32 v222, 1.0, v222
	v_add_f32_e32 v223, 1.0, v223
	v_add_f32_e32 v224, 1.0, v224
	v_add_f32_e32 v225, 1.0, v225
	v_rcp_f32_e32 v222, v222
	v_rcp_f32_e32 v223, v223
	v_rcp_f32_e32 v224, v224
	v_rcp_f32_e32 v225, v225
	v_pk_mul_f32 v[6:7], v[6:7], v[222:223]
	v_pk_mul_f32 v[8:9], v[8:9], v[224:225]
	v_cvt_pk_bf16_f32 v6, v6, v7
	v_cvt_pk_bf16_f32 v7, v8, v9
	s_waitcnt vmcnt(1)
	v_lshlrev_b32_e32 v210, 16, v206
	v_and_b32_e32 v211, 0xffff0000, v206
	v_lshlrev_b32_e32 v212, 16, v207
	v_and_b32_e32 v213, 0xffff0000, v207
	v_mul_f32_e32 v214, 0xbfb8aa3b, v210
	v_mul_f32_e32 v215, 0xbfb8aa3b, v211
	v_mul_f32_e32 v216, 0xbfb8aa3b, v212
	v_mul_f32_e32 v217, 0xbfb8aa3b, v213
	v_exp_f32_e32 v214, v214
	v_exp_f32_e32 v215, v215
	v_exp_f32_e32 v216, v216
	v_exp_f32_e32 v217, v217
	v_pk_mul_f32 v[10:11], v[10:11], v[210:211]
	v_pk_mul_f32 v[12:13], v[12:13], v[212:213]
	v_add_f32_e32 v214, 1.0, v214
	v_add_f32_e32 v215, 1.0, v215
	v_add_f32_e32 v216, 1.0, v216
	v_add_f32_e32 v217, 1.0, v217
	v_rcp_f32_e32 v214, v214
	v_rcp_f32_e32 v215, v215
	v_rcp_f32_e32 v216, v216
	v_rcp_f32_e32 v217, v217
	v_pk_mul_f32 v[10:11], v[10:11], v[214:215]
	v_pk_mul_f32 v[12:13], v[12:13], v[216:217]
	v_cvt_pk_bf16_f32 v10, v10, v11
	v_cvt_pk_bf16_f32 v11, v12, v13
	s_waitcnt vmcnt(0)
	v_lshlrev_b32_e32 v218, 16, v208
	v_and_b32_e32 v219, 0xffff0000, v208
	v_lshlrev_b32_e32 v220, 16, v209
	v_and_b32_e32 v221, 0xffff0000, v209
	v_mul_f32_e32 v222, 0xbfb8aa3b, v218
	v_mul_f32_e32 v223, 0xbfb8aa3b, v219
	v_mul_f32_e32 v224, 0xbfb8aa3b, v220
	v_mul_f32_e32 v225, 0xbfb8aa3b, v221
	v_exp_f32_e32 v222, v222
	v_exp_f32_e32 v223, v223
	v_exp_f32_e32 v224, v224
	v_exp_f32_e32 v225, v225
	v_pk_mul_f32 v[14:15], v[14:15], v[218:219]
	v_pk_mul_f32 v[16:17], v[16:17], v[220:221]
	v_add_f32_e32 v222, 1.0, v222
	v_add_f32_e32 v223, 1.0, v223
	v_add_f32_e32 v224, 1.0, v224
	v_add_f32_e32 v225, 1.0, v225
	v_rcp_f32_e32 v222, v222
	v_rcp_f32_e32 v223, v223
	v_rcp_f32_e32 v224, v224
	v_rcp_f32_e32 v225, v225
	v_pk_mul_f32 v[14:15], v[14:15], v[222:223]
	v_pk_mul_f32 v[16:17], v[16:17], v[224:225]
	v_cvt_pk_bf16_f32 v14, v14, v15
	v_cvt_pk_bf16_f32 v15, v16, v17
	global_store_dwordx2 v[138:139], v[50:51], off
	global_store_dwordx2 v[138:139], v[54:55], off offset:256
	global_store_dwordx2 v[138:139], v[58:59], off offset:512
	global_store_dwordx2 v[138:139], v[62:63], off offset:768
	global_store_dwordx2 v[138:139], v[34:35], off offset:1024
	global_store_dwordx2 v[138:139], v[38:39], off offset:1280
	global_store_dwordx2 v[138:139], v[42:43], off offset:1536
	global_store_dwordx2 v[138:139], v[46:47], off offset:1792
	global_store_dwordx2 v[142:143], v[18:19], off
	global_store_dwordx2 v[142:143], v[22:23], off offset:256
	global_store_dwordx2 v[142:143], v[26:27], off offset:512
	global_store_dwordx2 v[142:143], v[30:31], off offset:768
	global_store_dwordx2 v[142:143], v[2:3], off offset:1024
	global_store_dwordx2 v[142:143], v[6:7], off offset:1280
	global_store_dwordx2 v[142:143], v[10:11], off offset:1536
	global_store_dwordx2 v[142:143], v[14:15], off offset:1792
	s_branch .LBB0_177
